# grid barrier: every 8th arriver of an XCD issues an early non-blocking L2 writeback so the leader's final writeback has less to flush
# speedup vs baseline: 1.0013x; 1.0013x over previous
; __global__ void __launch_bounds__(NTHREADS, 2) mega(Params P) {
;     ...
;         if (ph > P.ph_lo && ph != 11 && ph != 23) grid.sync();
.Lxb_follower:
	s_add_i32 s5, s4, 1
	s_and_b32 s5, s5, 7
	s_cbranch_scc1 .Lxb_noearly
	buffer_wbl2 sc1
